# sb attention key tiles aligned to 64-key blocks so waves of a workgroup share K/V tiles in L1
# baseline (speedup 1.0000x reference)
; #define LAS __attribute__((address_space(3)))
; __device__ __forceinline__ float bflo(unsigned u) { return __uint_as_float(u << 16); }
; __device__ __forceinline__ float bfhi(unsigned u) { return __uint_as_float(u & 0xffff0000u); }
; __device__ __forceinline__ float sx(float v, int m, int lane) { return __builtin_bit_cast(float, __builtin_amdgcn_ds_bpermute((lane ^ m) << 2, __builtin_bit_cast(int, v))); }
; __device__ __forceinline__ void sb_item(const bf16_t* hbuf, const float* kmax2, bf16_t* mixed, LAS bf16_t* vT, int item, int lane) {
;     const int bh = item >> 10, qt = item & 1023, b = bh / 6, h = bh % 6, tq0 = qt * 16; const size_t row0 = (size_t)b * SEQ + tq0;
;     const int r = lane & 15, q = lane >> 4;
;     bf16x8 qf[2]; float bound, carry = 0.f;
;     const float km2 = kmax2[bh];
;     { float s = 0.f;
; #pragma unroll
;       for (int ks = 0; ks < 2; ++ks) { const u32x4 v = *(const u32x4*)(hbuf + (row0 + r) * INWP + C_SBQ + h * 64 + 32 * ks + 8 * q); qf[ks] = as_bf16x8(v);
;           s += bflo(v.x) * bflo(v.x) + bfhi(v.x) * bfhi(v.x) + bflo(v.y) * bflo(v.y) + bfhi(v.y) * bfhi(v.y) + bflo(v.z) * bflo(v.z) + bfhi(v.z) * bfhi(v.z) + bflo(v.w) * bflo(v.w) + bfhi(v.w) * bfhi(v.w); }
;       s += sx(s, 16, lane); s += sx(s, 32, lane);
;       bound = sqrtf(s * km2) * 0.125f * 1.01f + 0.05f; }
;     const int qpos = tq0 + r;
;     f32x4 O[4];
; #pragma unroll
;     for (int et = 0; et < 4; ++et) O[et] = (f32x4){0.f, 0.f, 0.f, 0.f};
;     const int cr = lane >> 3, dc = lane & 7;
;     const bf16_t* seqp = hbuf + (size_t)b * SEQ * INWP + h * 64;
;     u32x4 vreg[8], kreg[8];
;     { const int k0 = tq0 + 16 - 64;
; #pragma unroll
;       for (int i = 0; i < 8; ++i) vreg[i] = *(const u32x4*)(seqp + (size_t)max(k0 + cr + 8 * i, 0) * INWP + C_SBV + 8 * dc);
; #pragma unroll
;       for (int i = 0; i < 8; ++i) kreg[i] = *(const u32x4*)(seqp + (size_t)max(k0 + 16 * (i >> 1) + r, 0) * INWP + C_SBK + 32 * (i & 1) + 8 * q); }
.LBB0_191:
	s_ashr_i32 s0, s12, 10
	s_mul_hi_i32 s1, s0, 0x2aaaaaab
	s_lshr_b32 s15, s1, 31
	s_add_i32 s20, s1, s15
	s_mul_i32 s1, s20, 6
	s_sub_i32 s15, s0, s1
	s_lshl_b32 s1, s12, 4
	s_ashr_i32 s21, s20, 31
	s_and_b32 s17, s1, 0x3ff0
	s_lshl_b64 s[22:23], s[20:21], 14
	s_ashr_i32 s1, s0, 31
	s_or_b32 s21, s22, s17
	s_lshl_b64 s[0:1], s[0:1], 2
	s_add_u32 s0, s75, s0
	s_addc_u32 s1, s74, s1
	v_or_b32_e32 v126, s21, v34
	v_mov_b64_e32 v[8:9], s[42:43]
	s_lshl_b32 s72, s15, 6
	global_load_dword v16, v33, s[0:1] offset:1024
	v_mad_u64_u32 v[8:9], s[0:1], v126, s5, v[8:9]
	s_ashr_i32 s73, s72, 31
	v_mov_b32_e32 v127, s23
	v_mad_i32_i24 v9, s23, v207, v9
	s_lshl_b64 s[22:23], s[72:73], 1
	v_lshl_add_u64 v[8:9], v[8:9], 0, s[22:23]
	v_mov_b32_e32 v123, v33
	v_lshl_add_u64 v[12:13], v[8:9], 0, v[122:123]
	global_load_dwordx4 v[8:11], v[12:13], off offset:512
	s_mov_b32 s0, 0xf800000
	v_mov_b32_e32 v125, v33
	v_mov_b32_e32 v32, 0
	v_or_b32_e32 v138, s17, v34
	v_mov_b32_e32 v88, 0
	v_mov_b32_e32 v89, v32
	v_mov_b32_e32 v90, v32
	v_mov_b32_e32 v91, v32
	v_mov_b32_e32 v100, 0
	v_mov_b32_e32 v101, v32
	v_mov_b32_e32 v102, v32
	v_mov_b32_e32 v103, v32
	v_mov_b32_e32 v96, 0
	v_mov_b32_e32 v97, v32
	v_mov_b32_e32 v98, v32
	v_mov_b32_e32 v99, v32
	v_mov_b32_e32 v92, 0
	v_mov_b32_e32 v93, v32
	v_mov_b32_e32 v94, v32
	v_mov_b32_e32 v95, v32
	s_waitcnt vmcnt(0)
	v_and_b32_e32 v15, 0xffff0000, v8
	v_lshlrev_b32_e32 v14, 16, v8
	v_mul_f32_e32 v17, v15, v15
	v_fmac_f32_e32 v17, v14, v14
	v_lshlrev_b32_e32 v14, 16, v9
	v_fmac_f32_e32 v17, v14, v14
	v_and_b32_e32 v14, 0xffff0000, v9
	v_fmac_f32_e32 v17, v14, v14
	v_lshlrev_b32_e32 v14, 16, v10
	v_fmac_f32_e32 v17, v14, v14
	v_and_b32_e32 v14, 0xffff0000, v10
	v_fmac_f32_e32 v17, v14, v14
	v_lshlrev_b32_e32 v14, 16, v11
	v_fmac_f32_e32 v17, v14, v14
	v_and_b32_e32 v14, 0xffff0000, v11
	v_fmac_f32_e32 v17, v14, v14
	global_load_dwordx4 v[12:15], v[12:13], off offset:576
	s_waitcnt vmcnt(0)
	v_and_b32_e32 v19, 0xffff0000, v12
	v_lshlrev_b32_e32 v18, 16, v12
	v_mul_f32_e32 v19, v19, v19
	v_fmac_f32_e32 v19, v18, v18
	v_lshlrev_b32_e32 v18, 16, v13
	v_fmac_f32_e32 v19, v18, v18
	v_and_b32_e32 v18, 0xffff0000, v13
	v_fmac_f32_e32 v19, v18, v18
	v_lshlrev_b32_e32 v18, 16, v14
	v_fmac_f32_e32 v19, v18, v18
	v_and_b32_e32 v18, 0xffff0000, v14
	v_fmac_f32_e32 v19, v18, v18
	v_lshlrev_b32_e32 v18, 16, v15
	v_fmac_f32_e32 v19, v18, v18
	v_and_b32_e32 v18, 0xffff0000, v15
	v_fmac_f32_e32 v19, v18, v18
	v_add_f32_e32 v17, v17, v19
	ds_bpermute_b32 v18, v35, v17
	s_waitcnt lgkmcnt(0)
	v_add_f32_e32 v17, v17, v18
	ds_bpermute_b32 v18, v121, v17
	s_waitcnt lgkmcnt(0)
	v_add_f32_e32 v17, v17, v18
	v_mul_f32_e32 v16, v16, v17
	v_cmp_gt_f32_e32 vcc, s0, v16
	v_mul_f32_e32 v17, 0x4f800000, v16
	s_nop 0
	v_cndmask_b32_e32 v16, v16, v17, vcc
	v_sqrt_f32_e32 v17, v16
	s_nop 0
	v_add_u32_e32 v18, -1, v17
	v_fma_f32 v19, -v18, v17, v16
	v_cmp_ge_f32_e64 s[0:1], 0, v19
	v_add_u32_e32 v19, 1, v17
	s_nop 0
	v_cndmask_b32_e64 v18, v17, v18, s[0:1]
	v_fma_f32 v17, -v19, v17, v16
	v_cmp_lt_f32_e64 s[0:1], 0, v17
	s_nop 1
	v_cndmask_b32_e64 v17, v18, v19, s[0:1]
	s_mul_i32 s1, s20, 0x6000000
	s_mul_hi_i32 s0, s20, 0x6000000
	s_add_u32 s1, s42, s1
	v_mul_f32_e32 v18, 0x37800000, v17
	s_addc_u32 s15, s43, s0
	v_cndmask_b32_e32 v17, v17, v18, vcc
	v_cmp_class_f32_e32 vcc, v16, v209
	s_add_u32 s0, s1, s22
	s_addc_u32 s1, s15, s23
	v_cndmask_b32_e32 v16, v17, v16, vcc
	s_and_b32 s15, s17, 0xffffffc0
	v_mul_f32_e32 v16, 0x3e000000, v16
	v_or_b32_e32 v48, s15, v34
	v_or_b32_e32 v86, s15, v132
	v_fmamk_f32 v137, v16, 0x3f8147ae, v170
	v_max_i32_e32 v16, 0xffffffd0, v48
	v_max_i32_e32 v24, 0xffffffe0, v48
	v_max_i32_e32 v40, -16, v48
	v_max_i32_e32 v64, 0xffffffd8, v86
	v_max_i32_e32 v68, 0xffffffe0, v86
	v_add_u32_e32 v16, 48, v16
	v_mov_b64_e32 v[84:85], s[0:1]
	v_add_u32_e32 v24, 32, v24
	v_add_u32_e32 v40, 16, v40
	v_max_i32_e32 v48, 0, v48
	v_add_u32_e32 v64, 40, v64
	v_add_u32_e32 v68, 32, v68
	v_mad_u64_u32 v[16:17], s[20:21], v16, s5, v[84:85]
	v_mad_u64_u32 v[24:25], s[20:21], v24, s5, v[84:85]
	v_mad_u64_u32 v[40:41], s[20:21], v40, s5, v[84:85]
	v_mad_u64_u32 v[48:49], s[20:21], v48, s5, v[84:85]
	v_mad_u64_u32 v[64:65], s[20:21], v64, s5, v[84:85]
	v_mad_u64_u32 v[68:69], s[20:21], v68, s5, v[84:85]
	v_lshl_add_u64 v[20:21], v[16:17], 0, v[122:123]
	v_lshl_add_u64 v[28:29], v[24:25], 0, v[122:123]
	v_lshl_add_u64 v[44:45], v[40:41], 0, v[122:123]
	v_lshl_add_u64 v[52:53], v[48:49], 0, v[122:123]
	v_lshl_add_u64 v[64:65], v[64:65], 0, v[124:125]
	v_lshl_add_u64 v[68:69], v[68:69], 0, v[124:125]
	global_load_dwordx4 v[16:19], v[20:21], off offset:1344
	s_nop 0
	global_load_dwordx4 v[20:23], v[20:21], off offset:1280
	s_nop 0
	global_load_dwordx4 v[24:27], v[28:29], off offset:1344
	s_nop 0
	global_load_dwordx4 v[28:31], v[28:29], off offset:1280
	s_nop 0
	global_load_dwordx4 v[40:43], v[44:45], off offset:1344
	s_nop 0
	global_load_dwordx4 v[44:47], v[44:45], off offset:1280
	s_nop 0
	global_load_dwordx4 v[48:51], v[52:53], off offset:1344
	s_nop 0
	global_load_dwordx4 v[52:55], v[52:53], off offset:1280
	v_max_i32_e32 v76, -16, v86
	global_load_dwordx4 v[64:67], v[64:65], off offset:2048
	v_add_u32_e32 v76, 16, v76
	global_load_dwordx4 v[72:75], v[68:69], off offset:2048
	v_max_i32_e32 v68, 0xffffffe8, v86
	v_add_u32_e32 v68, 24, v68
	v_mad_u64_u32 v[68:69], s[20:21], v68, s5, v[84:85]
	v_mad_u64_u32 v[76:77], s[20:21], v76, s5, v[84:85]
	v_lshl_add_u64 v[68:69], v[68:69], 0, v[124:125]
	v_lshl_add_u64 v[76:77], v[76:77], 0, v[124:125]
	v_max_i32_e32 v56, 0xffffffc8, v86
	v_max_i32_e32 v60, 0xffffffd0, v86
	global_load_dwordx4 v[68:71], v[68:69], off offset:2048
	v_add_u32_e32 v56, 56, v56
	global_load_dwordx4 v[80:83], v[76:77], off offset:2048
	v_or_b32_e32 v76, 8, v86
	v_add_u32_e32 v60, 48, v60
	v_max_i32_e32 v76, 0, v76
	v_max_i32_e32 v86, 0, v86
	v_mad_u64_u32 v[56:57], s[20:21], v56, s5, v[84:85]
	v_mad_u64_u32 v[60:61], s[20:21], v60, s5, v[84:85]
	v_mad_u64_u32 v[76:77], s[20:21], v76, s5, v[84:85]
	v_mad_u64_u32 v[84:85], s[20:21], v86, s5, v[84:85]
	v_lshl_add_u64 v[56:57], v[56:57], 0, v[124:125]
	v_lshl_add_u64 v[60:61], v[60:61], 0, v[124:125]
	v_lshl_add_u64 v[76:77], v[76:77], 0, v[124:125]
	v_lshl_add_u64 v[84:85], v[84:85], 0, v[124:125]
	global_load_dwordx4 v[56:59], v[56:57], off offset:2048
	v_lshl_add_u64 v[128:129], s[0:1], 0, v[124:125]
	global_load_dwordx4 v[60:63], v[60:61], off offset:2048
	v_lshl_add_u64 v[130:131], s[0:1], 0, v[122:123]
	global_load_dwordx4 v[76:79], v[76:77], off offset:2048
	s_nop 0
	global_load_dwordx4 v[84:87], v[84:85], off offset:2048
	s_branch .LBB0_193

; #define LAS __attribute__((address_space(3)))
; __device__ __forceinline__ float bflo(unsigned u) { return __uint_as_float(u << 16); }
; __device__ __forceinline__ float bfhi(unsigned u) { return __uint_as_float(u & 0xffff0000u); }
; __device__ __forceinline__ float sx(float v, int m, int lane) { return __builtin_bit_cast(float, __builtin_amdgcn_ds_bpermute((lane ^ m) << 2, __builtin_bit_cast(int, v))); }
; __device__ __forceinline__ void sb_item(const bf16_t* hbuf, const float* kmax2, bf16_t* mixed, LAS bf16_t* vT, int item, int lane) {
;     const int bh = item >> 10, qt = item & 1023, b = bh / 6, h = bh % 6, tq0 = qt * 16; const size_t row0 = (size_t)b * SEQ + tq0;
;     const int r = lane & 15, q = lane >> 4;
;     bf16x8 qf[2]; float bound, carry = 0.f;
;     const float km2 = kmax2[bh];
;     { float s = 0.f;
; #pragma unroll
;       for (int ks = 0; ks < 2; ++ks) { const u32x4 v = *(const u32x4*)(hbuf + (row0 + r) * INWP + C_SBQ + h * 64 + 32 * ks + 8 * q); qf[ks] = as_bf16x8(v);
;           s += bflo(v.x) * bflo(v.x) + bfhi(v.x) * bfhi(v.x) + bflo(v.y) * bflo(v.y) + bfhi(v.y) * bfhi(v.y) + bflo(v.z) * bflo(v.z) + bfhi(v.z) * bfhi(v.z) + bflo(v.w) * bflo(v.w) + bfhi(v.w) * bfhi(v.w); }
;       s += sx(s, 16, lane); s += sx(s, 32, lane);
;       bound = sqrtf(s * km2) * 0.125f * 1.01f + 0.05f; }
;     const int qpos = tq0 + r;
;     f32x4 O[4];
; #pragma unroll
;     for (int et = 0; et < 4; ++et) O[et] = (f32x4){0.f, 0.f, 0.f, 0.f};
;     const int cr = lane >> 3, dc = lane & 7;
;     const bf16_t* seqp = hbuf + (size_t)b * SEQ * INWP + h * 64;
;     u32x4 vreg[8], kreg[8];
;     { const int k0 = tq0 + 16 - 64;
; #pragma unroll
;       for (int i = 0; i < 8; ++i) vreg[i] = *(const u32x4*)(seqp + (size_t)max(k0 + cr + 8 * i, 0) * INWP + C_SBV + 8 * dc);
; #pragma unroll
;       for (int i = 0; i < 8; ++i) kreg[i] = *(const u32x4*)(seqp + (size_t)max(k0 + 16 * (i >> 1) + r, 0) * INWP + C_SBK + 32 * (i & 1) + 8 * q); }
.LBB0_234:
	s_and_b32 s98, s12, 3
	s_lshl_b32 s98, s98, 3
	s_bfe_u32 s99, s12, 0x30002
	s_add_i32 s98, s98, s99
	s_and_b32 s99, s12, 0xffffffe0
	s_or_b32 s98, s98, s99
	s_ashr_i32 s0, s98, 10
	s_mul_hi_i32 s1, s0, 0x2aaaaaab
	s_lshr_b32 s17, s1, 31
	s_add_i32 s20, s1, s17
	s_mul_i32 s1, s20, 6
	s_sub_i32 s17, s0, s1
	s_lshl_b32 s1, s98, 4
	s_ashr_i32 s21, s20, 31
	s_and_b32 s26, s1, 0x3ff0
	s_lshl_b64 s[22:23], s[20:21], 14
	s_ashr_i32 s1, s0, 31
	s_or_b32 s21, s22, s26
	s_lshl_b64 s[0:1], s[0:1], 2
	s_add_u32 s0, s75, s0
	s_addc_u32 s1, s74, s1
	v_or_b32_e32 v34, s21, v122
	v_mov_b64_e32 v[8:9], s[42:43]
	s_lshl_b32 s72, s17, 6
	global_load_dword v16, v33, s[0:1] offset:1024
	v_mad_u64_u32 v[8:9], s[0:1], v34, s5, v[8:9]
	s_ashr_i32 s73, s72, 31
	v_mov_b32_e32 v35, s23
	v_mad_i32_i24 v9, s23, v207, v9
	s_lshl_b64 s[22:23], s[72:73], 1
	v_lshl_add_u64 v[8:9], v[8:9], 0, s[22:23]
	v_lshlrev_b32_e32 v32, 1, v124
	v_lshl_add_u64 v[12:13], v[8:9], 0, v[32:33]
	global_load_dwordx4 v[8:11], v[12:13], off offset:512
	s_mov_b32 s0, 0xf800000
	v_lshlrev_b32_e32 v88, 1, v126
	v_mov_b32_e32 v89, v33
	v_mov_b32_e32 v153, 0
	v_or_b32_e32 v155, s26, v122
	v_mov_b32_e32 v100, 0
	v_mov_b32_e32 v101, v153
	v_mov_b32_e32 v102, v153
	v_mov_b32_e32 v103, v153
	v_mov_b32_e32 v96, 0
	v_mov_b32_e32 v97, v153
	v_mov_b32_e32 v98, v153
	v_mov_b32_e32 v99, v153
	v_mov_b32_e32 v92, 0
	v_mov_b32_e32 v93, v153
	v_mov_b32_e32 v94, v153
	v_mov_b32_e32 v95, v153
	v_mov_b32_e32 v90, v153
	v_mov_b32_e32 v91, v153
	s_waitcnt vmcnt(0)
	v_and_b32_e32 v15, 0xffff0000, v8
	v_lshlrev_b32_e32 v14, 16, v8
	v_mul_f32_e32 v17, v15, v15
	v_fmac_f32_e32 v17, v14, v14
	v_lshlrev_b32_e32 v14, 16, v9
	v_fmac_f32_e32 v17, v14, v14
	v_and_b32_e32 v14, 0xffff0000, v9
	v_fmac_f32_e32 v17, v14, v14
	v_lshlrev_b32_e32 v14, 16, v10
	v_fmac_f32_e32 v17, v14, v14
	v_and_b32_e32 v14, 0xffff0000, v10
	v_fmac_f32_e32 v17, v14, v14
	v_lshlrev_b32_e32 v14, 16, v11
	v_fmac_f32_e32 v17, v14, v14
	v_and_b32_e32 v14, 0xffff0000, v11
	v_fmac_f32_e32 v17, v14, v14
	global_load_dwordx4 v[12:15], v[12:13], off offset:576
	s_waitcnt vmcnt(0)
	v_and_b32_e32 v19, 0xffff0000, v12
	v_lshlrev_b32_e32 v18, 16, v12
	v_mul_f32_e32 v19, v19, v19
	v_fmac_f32_e32 v19, v18, v18
	v_lshlrev_b32_e32 v18, 16, v13
	v_fmac_f32_e32 v19, v18, v18
	v_and_b32_e32 v18, 0xffff0000, v13
	v_fmac_f32_e32 v19, v18, v18
	v_lshlrev_b32_e32 v18, 16, v14
	v_fmac_f32_e32 v19, v18, v18
	v_and_b32_e32 v18, 0xffff0000, v14
	v_fmac_f32_e32 v19, v18, v18
	v_lshlrev_b32_e32 v18, 16, v15
	v_fmac_f32_e32 v19, v18, v18
	v_and_b32_e32 v18, 0xffff0000, v15
	v_fmac_f32_e32 v19, v18, v18
	v_add_f32_e32 v17, v17, v19
	ds_bpermute_b32 v18, v132, v17
	s_waitcnt lgkmcnt(0)
	v_add_f32_e32 v17, v17, v18
	ds_bpermute_b32 v18, v133, v17
	s_waitcnt lgkmcnt(0)
	v_add_f32_e32 v17, v17, v18
	v_mul_f32_e32 v16, v16, v17
	v_cmp_gt_f32_e32 vcc, s0, v16
	v_mul_f32_e32 v17, 0x4f800000, v16
	s_nop 0
	v_cndmask_b32_e32 v16, v16, v17, vcc
	v_sqrt_f32_e32 v17, v16
	s_nop 0
	v_add_u32_e32 v18, -1, v17
	v_fma_f32 v19, -v18, v17, v16
	v_cmp_ge_f32_e64 s[0:1], 0, v19
	v_add_u32_e32 v19, 1, v17
	s_nop 0
	v_cndmask_b32_e64 v18, v17, v18, s[0:1]
	v_fma_f32 v17, -v19, v17, v16
	v_cmp_lt_f32_e64 s[0:1], 0, v17
	s_nop 1
	v_cndmask_b32_e64 v17, v18, v19, s[0:1]
	s_mul_i32 s1, s20, 0x6000000
	s_mul_hi_i32 s0, s20, 0x6000000
	s_add_u32 s1, s42, s1
	v_mul_f32_e32 v18, 0x37800000, v17
	s_addc_u32 s17, s43, s0
	v_cndmask_b32_e32 v17, v17, v18, vcc
	v_cmp_class_f32_e32 vcc, v16, v209
	s_add_u32 s0, s1, s22
	s_addc_u32 s1, s17, s23
	v_cndmask_b32_e32 v16, v17, v16, vcc
	s_and_b32 s17, s26, 0xffffffc0
	v_mul_f32_e32 v16, 0x3e000000, v16
	v_or_b32_e32 v48, s17, v122
	v_or_b32_e32 v86, s17, v134
	v_fmamk_f32 v154, v16, 0x3f8147ae, v170
	v_max_i32_e32 v16, 0xffffffd0, v48
	v_max_i32_e32 v24, 0xffffffe0, v48
	v_max_i32_e32 v40, -16, v48
	v_max_i32_e32 v64, 0xffffffd8, v86
	v_max_i32_e32 v68, 0xffffffe0, v86
	v_add_u32_e32 v16, 48, v16
	v_mov_b64_e32 v[84:85], s[0:1]
	v_add_u32_e32 v24, 32, v24
	v_add_u32_e32 v40, 16, v40
	v_max_i32_e32 v48, 0, v48
	v_add_u32_e32 v64, 40, v64
	v_add_u32_e32 v68, 32, v68
	v_mad_u64_u32 v[16:17], s[20:21], v16, s5, v[84:85]
	v_mad_u64_u32 v[24:25], s[20:21], v24, s5, v[84:85]
	v_mad_u64_u32 v[40:41], s[20:21], v40, s5, v[84:85]
	v_mad_u64_u32 v[48:49], s[20:21], v48, s5, v[84:85]
	v_mad_u64_u32 v[64:65], s[20:21], v64, s5, v[84:85]
	v_mad_u64_u32 v[68:69], s[20:21], v68, s5, v[84:85]
	v_lshl_add_u64 v[20:21], v[16:17], 0, v[32:33]
	v_lshl_add_u64 v[28:29], v[24:25], 0, v[32:33]
	v_lshl_add_u64 v[44:45], v[40:41], 0, v[32:33]
	v_lshl_add_u64 v[52:53], v[48:49], 0, v[32:33]
	v_lshl_add_u64 v[64:65], v[64:65], 0, v[88:89]
	v_lshl_add_u64 v[68:69], v[68:69], 0, v[88:89]
	global_load_dwordx4 v[16:19], v[20:21], off offset:1344
	s_nop 0
	global_load_dwordx4 v[20:23], v[20:21], off offset:1280
	s_nop 0
	global_load_dwordx4 v[24:27], v[28:29], off offset:1344
	s_nop 0
	global_load_dwordx4 v[28:31], v[28:29], off offset:1280
	s_nop 0
	global_load_dwordx4 v[40:43], v[44:45], off offset:1344
	s_nop 0
	global_load_dwordx4 v[44:47], v[44:45], off offset:1280
	s_nop 0
	global_load_dwordx4 v[48:51], v[52:53], off offset:1344
	s_nop 0
	global_load_dwordx4 v[52:55], v[52:53], off offset:1280
	v_max_i32_e32 v76, -16, v86
	global_load_dwordx4 v[64:67], v[64:65], off offset:2048
	v_add_u32_e32 v76, 16, v76
	global_load_dwordx4 v[72:75], v[68:69], off offset:2048
	v_max_i32_e32 v68, 0xffffffe8, v86
	v_add_u32_e32 v68, 24, v68
	v_mad_u64_u32 v[68:69], s[20:21], v68, s5, v[84:85]
	v_mad_u64_u32 v[76:77], s[20:21], v76, s5, v[84:85]
	v_lshl_add_u64 v[68:69], v[68:69], 0, v[88:89]
	v_lshl_add_u64 v[76:77], v[76:77], 0, v[88:89]
	v_max_i32_e32 v56, 0xffffffc8, v86
	v_max_i32_e32 v60, 0xffffffd0, v86
	global_load_dwordx4 v[68:71], v[68:69], off offset:2048
	v_add_u32_e32 v56, 56, v56
	global_load_dwordx4 v[80:83], v[76:77], off offset:2048
	v_or_b32_e32 v76, 8, v86
	v_add_u32_e32 v60, 48, v60
	v_max_i32_e32 v76, 0, v76
	v_max_i32_e32 v86, 0, v86
	v_mad_u64_u32 v[56:57], s[20:21], v56, s5, v[84:85]
	v_mad_u64_u32 v[60:61], s[20:21], v60, s5, v[84:85]
	v_mad_u64_u32 v[76:77], s[20:21], v76, s5, v[84:85]
	v_mad_u64_u32 v[84:85], s[20:21], v86, s5, v[84:85]
	v_lshl_add_u64 v[56:57], v[56:57], 0, v[88:89]
	v_lshl_add_u64 v[60:61], v[60:61], 0, v[88:89]
	v_lshl_add_u64 v[76:77], v[76:77], 0, v[88:89]
	v_lshl_add_u64 v[84:85], v[84:85], 0, v[88:89]
	global_load_dwordx4 v[56:59], v[56:57], off offset:2048
	v_lshl_add_u64 v[128:129], s[0:1], 0, v[88:89]
	global_load_dwordx4 v[60:63], v[60:61], off offset:2048
	v_lshl_add_u64 v[130:131], s[0:1], 0, v[32:33]
	global_load_dwordx4 v[76:79], v[76:77], off offset:2048
	v_mov_b32_e32 v88, 0
	global_load_dwordx4 v[84:87], v[84:85], off offset:2048
	v_mov_b32_e32 v89, v153
	s_branch .LBB0_236

; #define LAS __attribute__((address_space(3)))
; __device__ __forceinline__ float bflo(unsigned u) { return __uint_as_float(u << 16); }
; __device__ __forceinline__ float bfhi(unsigned u) { return __uint_as_float(u & 0xffff0000u); }
; __device__ __forceinline__ float sx(float v, int m, int lane) { return __builtin_bit_cast(float, __builtin_amdgcn_ds_bpermute((lane ^ m) << 2, __builtin_bit_cast(int, v))); }
; __device__ __forceinline__ void sb_item(const bf16_t* hbuf, const float* kmax2, bf16_t* mixed, LAS bf16_t* vT, int item, int lane) {
;     const int bh = item >> 10, qt = item & 1023, b = bh / 6, h = bh % 6, tq0 = qt * 16; const size_t row0 = (size_t)b * SEQ + tq0;
;     const int r = lane & 15, q = lane >> 4;
;     bf16x8 qf[2]; float bound, carry = 0.f;
;     const float km2 = kmax2[bh];
;     { float s = 0.f;
; #pragma unroll
;       for (int ks = 0; ks < 2; ++ks) { const u32x4 v = *(const u32x4*)(hbuf + (row0 + r) * INWP + C_SBQ + h * 64 + 32 * ks + 8 * q); qf[ks] = as_bf16x8(v);
;           s += bflo(v.x) * bflo(v.x) + bfhi(v.x) * bfhi(v.x) + bflo(v.y) * bflo(v.y) + bfhi(v.y) * bfhi(v.y) + bflo(v.z) * bflo(v.z) + bfhi(v.z) * bfhi(v.z) + bflo(v.w) * bflo(v.w) + bfhi(v.w) * bfhi(v.w); }
;       s += sx(s, 16, lane); s += sx(s, 32, lane);
;       bound = sqrtf(s * km2) * 0.125f * 1.01f + 0.05f; }
;     const int qpos = tq0 + r;
;     f32x4 O[4];
; #pragma unroll
;     for (int et = 0; et < 4; ++et) O[et] = (f32x4){0.f, 0.f, 0.f, 0.f};
;     const int cr = lane >> 3, dc = lane & 7;
;     const bf16_t* seqp = hbuf + (size_t)b * SEQ * INWP + h * 64;
;     u32x4 vreg[8], kreg[8];
;     { const int k0 = tq0 + 16 - 64;
; #pragma unroll
;       for (int i = 0; i < 8; ++i) vreg[i] = *(const u32x4*)(seqp + (size_t)max(k0 + cr + 8 * i, 0) * INWP + C_SBV + 8 * dc);
; #pragma unroll
;       for (int i = 0; i < 8; ++i) kreg[i] = *(const u32x4*)(seqp + (size_t)max(k0 + 16 * (i >> 1) + r, 0) * INWP + C_SBK + 32 * (i & 1) + 8 * q); }
.LBB0_283:
	s_ashr_i32 s20, s15, 10
	s_mul_hi_i32 s0, s20, 0x2aaaaaab
	s_lshr_b32 s1, s0, 31
	s_add_i32 s0, s0, s1
	s_mul_i32 s1, s0, 6
	s_sub_i32 s17, s20, s1
	s_lshl_b32 s1, s15, 4
	s_and_b32 s26, s1, 0x3ff0
	s_ashr_i32 s1, s0, 31
	s_lshl_b64 s[22:23], s[0:1], 14
	s_ashr_i32 s21, s20, 31
	s_or_b32 s22, s22, s26
	s_lshl_b64 s[20:21], s[20:21], 2
	s_add_u32 s38, s75, s20
	v_lshl_add_u64 v[124:125], s[22:23], 0, v[122:123]
	v_mov_b64_e32 v[4:5], s[42:43]
	s_addc_u32 s39, s74, s21
	v_mad_u64_u32 v[4:5], s[20:21], v124, s5, v[4:5]
	v_mov_b32_e32 v6, v5
	v_mad_u64_u32 v[6:7], s[20:21], v125, s5, v[6:7]
	s_lshl_b32 s20, s17, 6
	s_ashr_i32 s21, s20, 31
	v_mov_b32_e32 v5, v6
	s_lshl_b64 s[22:23], s[20:21], 1
	v_lshl_add_u64 v[4:5], v[4:5], 0, s[22:23]
	s_waitcnt vmcnt(0)
	v_lshl_add_u64 v[8:9], v[4:5], 0, v[116:117]
	global_load_dwordx4 v[4:7], v[8:9], off offset:512
	global_load_dword v54, v33, s[38:39] offset:1024
	s_mul_hi_i32 s1, s0, 0x6000000
	global_load_dwordx4 v[8:11], v[8:9], off offset:576
	s_mul_i32 s0, s0, 0x6000000
	s_add_u32 s0, s42, s0
	s_addc_u32 s1, s43, s1
	s_add_u32 s22, s0, s22
	s_addc_u32 s23, s1, s23
	s_and_b32 s17, s26, 0xffffffc0
	v_or_b32_e32 v12, s17, v130
	s_waitcnt vmcnt(0)
	v_or_b32_e32 v55, s17, v134
	v_mov_b64_e32 v[48:49], s[22:23]
	v_max_i32_e32 v13, 0xffffffd0, v12
	v_max_i32_e32 v14, 0xffffffe0, v12
	v_max_i32_e32 v15, -16, v12
	v_max_i32_e32 v12, 0, v12
	v_max_i32_e32 v16, 0xffffffc8, v55
	v_max_i32_e32 v17, 0xffffffd0, v55
	v_max_i32_e32 v18, 0xffffffd8, v55
	v_max_i32_e32 v19, 0xffffffe0, v55
	v_add_u32_e32 v20, 48, v13
	v_add_u32_e32 v21, 32, v14
	v_add_u32_e32 v22, 16, v15
	v_mad_u64_u32 v[12:13], s[0:1], v12, s5, v[48:49]
	v_add_u32_e32 v23, 56, v16
	v_add_u32_e32 v24, 48, v17
	v_add_u32_e32 v26, 40, v18
	v_add_u32_e32 v28, 32, v19
	v_mad_u64_u32 v[14:15], s[0:1], v20, s5, v[48:49]
	v_mad_u64_u32 v[16:17], s[0:1], v21, s5, v[48:49]
	v_mad_u64_u32 v[18:19], s[0:1], v22, s5, v[48:49]
	v_lshl_add_u64 v[20:21], v[12:13], 0, v[116:117]
	v_mad_u64_u32 v[22:23], s[0:1], v23, s5, v[48:49]
	v_mad_u64_u32 v[24:25], s[0:1], v24, s5, v[48:49]
	v_mad_u64_u32 v[26:27], s[0:1], v26, s5, v[48:49]
	v_mad_u64_u32 v[28:29], s[0:1], v28, s5, v[48:49]
	v_lshl_add_u64 v[30:31], v[14:15], 0, v[116:117]
	v_lshl_add_u64 v[40:41], v[16:17], 0, v[116:117]
	v_lshl_add_u64 v[42:43], v[18:19], 0, v[116:117]
	global_load_dwordx4 v[12:15], v[20:21], off offset:1344
	global_load_dwordx4 v[16:19], v[20:21], off offset:1280
	v_lshl_add_u64 v[20:21], v[22:23], 0, v[118:119]
	v_lshl_add_u64 v[22:23], v[24:25], 0, v[118:119]
	v_lshl_add_u64 v[44:45], v[26:27], 0, v[118:119]
	v_lshl_add_u64 v[50:51], v[28:29], 0, v[118:119]
	global_load_dwordx4 v[68:71], v[30:31], off offset:1344
	global_load_dwordx4 v[72:75], v[30:31], off offset:1280
	global_load_dwordx4 v[56:59], v[40:41], off offset:1344
	global_load_dwordx4 v[60:63], v[40:41], off offset:1280
	s_nop 0
	global_load_dwordx4 v[28:31], v[42:43], off offset:1344
	s_nop 0
	global_load_dwordx4 v[40:43], v[42:43], off offset:1280
	s_nop 0
	global_load_dwordx4 v[24:27], v[20:21], off offset:2048
	s_nop 0
	global_load_dwordx4 v[20:23], v[22:23], off offset:2048
	v_mov_b32_e32 v142, 0
	v_or_b32_e32 v144, s26, v130
	v_lshl_add_u64 v[126:127], s[22:23], 0, v[118:119]
	v_lshl_add_u64 v[128:129], s[22:23], 0, v[116:117]
	v_mov_b32_e32 v76, 0
	v_mov_b32_e32 v77, v142
	v_mov_b32_e32 v78, v142
	v_mov_b32_e32 v79, v142
	v_mov_b32_e32 v65, v142
	v_mov_b32_e32 v66, v142
	v_mov_b32_e32 v67, v142
	v_and_b32_e32 v47, 0xffff0000, v4
	v_lshlrev_b32_e32 v46, 16, v4
	v_mul_f32_e32 v64, v47, v47
	v_lshlrev_b32_e32 v52, 16, v5
	v_fmac_f32_e32 v64, v46, v46
	global_load_dwordx4 v[44:47], v[44:45], off offset:2048
	s_nop 0
	global_load_dwordx4 v[80:83], v[50:51], off offset:2048
	v_max_i32_e32 v50, 0xffffffe8, v55
	v_fmac_f32_e32 v64, v52, v52
	v_add_u32_e32 v50, 24, v50
	v_max_i32_e32 v52, -16, v55
	v_and_b32_e32 v53, 0xffff0000, v5
	v_mad_u64_u32 v[50:51], s[0:1], v50, s5, v[48:49]
	v_add_u32_e32 v52, 16, v52
	v_fmac_f32_e32 v64, v53, v53
	v_lshl_add_u64 v[50:51], v[50:51], 0, v[118:119]
	v_mad_u64_u32 v[52:53], s[0:1], v52, s5, v[48:49]
	v_lshl_add_u64 v[52:53], v[52:53], 0, v[118:119]
	global_load_dwordx4 v[88:91], v[50:51], off offset:2048
	global_load_dwordx4 v[84:87], v[52:53], off offset:2048
	v_or_b32_e32 v50, 8, v55
	v_max_i32_e32 v50, 0, v50
	v_mad_u64_u32 v[50:51], s[0:1], v50, s5, v[48:49]
	v_max_i32_e32 v52, 0, v55
	v_lshl_add_u64 v[50:51], v[50:51], 0, v[118:119]
	v_mad_u64_u32 v[48:49], s[0:1], v52, s5, v[48:49]
	v_lshl_add_u64 v[48:49], v[48:49], 0, v[118:119]
	global_load_dwordx4 v[92:95], v[50:51], off offset:2048
	global_load_dwordx4 v[96:99], v[48:49], off offset:2048
	v_lshlrev_b32_e32 v48, 16, v6
	v_fmac_f32_e32 v64, v48, v48
	v_and_b32_e32 v48, 0xffff0000, v6
	v_fmac_f32_e32 v64, v48, v48
	v_lshlrev_b32_e32 v48, 16, v7
	v_fmac_f32_e32 v64, v48, v48
	v_and_b32_e32 v48, 0xffff0000, v7
	v_and_b32_e32 v49, 0xffff0000, v8
	v_fmac_f32_e32 v64, v48, v48
	v_lshlrev_b32_e32 v48, 16, v8
	v_mul_f32_e32 v49, v49, v49
	v_fmac_f32_e32 v49, v48, v48
	v_lshlrev_b32_e32 v48, 16, v9
	v_fmac_f32_e32 v49, v48, v48
	v_and_b32_e32 v48, 0xffff0000, v9
	v_fmac_f32_e32 v49, v48, v48
	v_lshlrev_b32_e32 v48, 16, v10
	v_fmac_f32_e32 v49, v48, v48
	v_and_b32_e32 v48, 0xffff0000, v10
	v_fmac_f32_e32 v49, v48, v48
	v_lshlrev_b32_e32 v48, 16, v11
	v_fmac_f32_e32 v49, v48, v48
	v_and_b32_e32 v48, 0xffff0000, v11
	v_fmac_f32_e32 v49, v48, v48
	v_add_f32_e32 v48, v64, v49
	ds_bpermute_b32 v49, v132, v48
	s_mov_b32 s0, 0xf800000
	v_mov_b32_e32 v64, 0
	v_mov_b32_e32 v52, 0
	v_mov_b32_e32 v53, v142
	s_waitcnt lgkmcnt(0)
	v_add_f32_e32 v48, v48, v49
	ds_bpermute_b32 v49, v133, v48
	v_mov_b32_e32 v55, v142
	s_waitcnt lgkmcnt(0)
	v_add_f32_e32 v48, v48, v49
	v_mul_f32_e32 v48, v54, v48
	v_mul_f32_e32 v49, 0x4f800000, v48
	v_cmp_gt_f32_e32 vcc, s0, v48
	v_mov_b32_e32 v54, v142
	s_nop 0
	v_cndmask_b32_e32 v48, v48, v49, vcc
	v_sqrt_f32_e32 v49, v48
	s_nop 0
	v_add_u32_e32 v50, -1, v49
	v_fma_f32 v51, -v50, v49, v48
	v_cmp_ge_f32_e64 s[0:1], 0, v51
	v_add_u32_e32 v51, 1, v49
	s_nop 0
	v_cndmask_b32_e64 v50, v49, v50, s[0:1]
	v_fma_f32 v49, -v51, v49, v48
	v_cmp_lt_f32_e64 s[0:1], 0, v49
	s_nop 1
	v_cndmask_b32_e64 v49, v50, v51, s[0:1]
	v_mul_f32_e32 v50, 0x37800000, v49
	v_cndmask_b32_e32 v49, v49, v50, vcc
	v_cmp_class_f32_e32 vcc, v48, v209
	v_mov_b32_e32 v50, v142
	v_mov_b32_e32 v51, v142
	v_cndmask_b32_e32 v48, v49, v48, vcc
	v_mul_f32_e32 v48, 0x3e000000, v48
	v_fmamk_f32 v143, v48, 0x3f8147ae, v170
	v_mov_b32_e32 v48, 0
	v_mov_b32_e32 v49, v142
	s_branch .LBB0_285
